# v12 + head-major Q/K/V/O layout [head][token][64] (EpiWin stores, attention loads/stores, attn_combine loads)
# speedup vs baseline: 1.0019x; 1.0019x over previous
; __device__ __forceinline__ int ltid(int wave) { int t = (wave << 6) | (int)__builtin_amdgcn_mbcnt_hi(~0u, __builtin_amdgcn_mbcnt_lo(~0u, 0u)); asm volatile("" : "+v"(t)); return t; }
; __device__ __forceinline__ int lbid() { int b = blockIdx.x; asm volatile("" : "+s"(b)); return b; }
; __device__ __forceinline__ u32x4 pack8(f32x4 v0, f32x4 v1) { u32x4 w; w.x = cvt_pk_bf16(v0[0], v0[1]); w.y = cvt_pk_bf16(v0[2], v0[3]); w.z = cvt_pk_bf16(v1[0], v1[1]); w.w = cvt_pk_bf16(v1[2], v1[3]); return w; }
; __device__ __forceinline__ void unpack8(u32x4 w, f32x4& v0, f32x4& v1) { v0 = (f32x4){bflo(w.x), bfhi(w.x), bflo(w.y), bfhi(w.y)}; v1 = (f32x4){bflo(w.z), bfhi(w.z), bflo(w.w), bfhi(w.w)}; }
; __device__ void attn_combine(const Params& p) {
;     const bf16_t* Ab = (const bf16_t*)(p.ws + B_Q); const float* LSE = (const float*)(p.ws + SM_LSE); bf16_t* YA = (bf16_t*)(p.ws + B_YATT);
;     for (int e = lbid() * 512 + ltid(p.wave); e < MT * 64; e += gridDim.x * 512) {
;         const int tok = e >> 6, h = (e >> 3) & 7, c8 = e & 7;
;         const float l0 = LSE[(size_t)tok * 24 + h], l1 = LSE[(size_t)tok * 24 + 8 + h], l2 = LSE[(size_t)tok * 24 + 16 + h];
;         const float m = fmaxf(l0, fmaxf(l1, l2)); float w0 = __expf(l0 - m), w1 = __expf(l1 - m), w2 = __expf(l2 - m); const float inv = 1.0f / (w0 + w1 + w2); w0 *= inv; w1 *= inv; w2 *= inv;
;         f32x4 a0, a1, b0, b1, c0, c1;
;         const u32x4 ua = *(const u32x4*)(Ab + (size_t)tok * 1536 + h * 64 + c8 * 8), ub = *(const u32x4*)(Ab + (size_t)tok * 1536 + (8 + h) * 64 + c8 * 8), uc = *(const u32x4*)(Ab + (size_t)tok * 1536 + (16 + h) * 64 + c8 * 8);
;         asm volatile("" ::: "memory");
;         unpack8(ua, a0, a1); unpack8(ub, b0, b1); unpack8(uc, c0, c1);
;         *(u32x4*)(YA + (size_t)tok * 512 + h * 64 + c8 * 8) = pack8(a0 * w0 + b0 * w1 + c0 * w2, a1 * w0 + b1 * w1 + c1 * w2);
;     }
.LBB0_256:
	s_mov_b32 s0, s80
	v_mov_b32_e32 v0, v60
	s_mov_b32 s1, 0x180000
	s_waitcnt lgkmcnt(0)
	v_lshl_add_u32 v2, s0, 9, v0
	v_cmp_gt_i32_e32 vcc, s1, v2
	s_and_saveexec_b64 s[36:37], vcc
	v_readlane_b32 s6, v254, 29
	v_readlane_b32 s4, v252, 19
	v_readlane_b32 s7, v254, 30
	v_readlane_b32 s5, v252, 20
	v_readlane_b32 s7, v253, 62
	s_movk_i32 s8, 0x80
	s_cbranch_execz .LBB0_259
	v_lshlrev_b32_e32 v0, 3, v0
	v_lshl_add_u32 v3, s0, 12, v0
	s_mov_b64 s[38:39], 0
.LBB0_258:
	v_ashrrev_i32_e32 v16, 6, v2
	v_bfe_u32 v8, v2, 3, 3
	v_mov_b64_e32 v[4:5], s[88:89]
	v_mad_i64_i32 v[4:5], s[0:1], v16, s82, v[4:5]
	v_lshlrev_b32_e32 v0, 2, v8
	v_lshl_add_u64 v[4:5], v[4:5], 0, v[0:1]
	global_load_dword v20, v[4:5], off
	global_load_dword v21, v[4:5], off offset:32
	global_load_dword v22, v[4:5], off offset:64
	v_mov_b64_e32 v[6:7], s[90:91]
	v_and_b32_e32 v9, 56, v3
	v_mad_i64_i32 v[6:7], s[0:1], v16, s8, v[6:7]
	v_lshlrev_b32_e32 v0, 7, v8
	v_mov_b32_e32 v19, v1
	v_lshlrev_b32_e32 v18, 1, v9
	v_mul_u32_u24_e32 v4, 0x300000, v8
	v_mov_b32_e32 v5, v1
	s_mov_b64 s[0:1], 0x1800000
	v_lshl_add_u64 v[4:5], v[6:7], 0, v[4:5]
	v_lshl_add_u64 v[12:13], v[4:5], 0, v[18:19]
	v_lshl_add_u64 v[8:9], v[12:13], 0, s[0:1]
	global_load_dwordx4 v[4:7], v[12:13], off
	v_lshl_add_u64 v[12:13], v[8:9], 0, s[0:1]
	global_load_dwordx4 v[8:11], v[8:9], off
	global_load_dwordx4 v[12:15], v[12:13], off
	v_ashrrev_i32_e32 v17, 31, v16
	v_lshlrev_b64 v[16:17], 10, v[16:17]
	v_lshl_add_u64 v[16:17], s[4:5], 0, v[16:17]
	v_lshl_add_u64 v[16:17], v[16:17], 0, v[0:1]
	v_lshl_add_u64 v[16:17], v[16:17], 0, v[18:19]
	v_add_u32_e32 v2, s6, v2
	s_mov_b32 s0, 0x17ffff
	v_cmp_lt_i32_e32 vcc, s0, v2
	s_or_b64 s[38:39], vcc, s[38:39]
	v_add_u32_e32 v3, s7, v3
	s_waitcnt vmcnt(0)
	v_max3_f32 v0, v20, v21, v22
	v_sub_f32_e32 v18, v20, v0
	v_sub_f32_e32 v19, v21, v0
	v_sub_f32_e32 v0, v22, v0
	v_mul_f32_e32 v30, 0x3fb8aa3b, v18
	v_mul_f32_e32 v31, 0x3fb8aa3b, v19
	v_mul_f32_e32 v0, 0x3fb8aa3b, v0
	v_exp_f32_e32 v30, v30
	v_exp_f32_e32 v31, v31
	v_exp_f32_e32 v32, v0
	v_lshlrev_b32_e32 v22, 16, v8
	v_and_b32_e32 v23, 0xffff0000, v8
	v_add_f32_e32 v0, v30, v31
	v_add_f32_e32 v0, v32, v0
	v_div_scale_f32 v33, s[0:1], v0, v0, 1.0
	v_rcp_f32_e32 v35, v33
	v_div_scale_f32 v34, vcc, 1.0, v0, 1.0
	v_lshlrev_b32_e32 v8, 16, v9
	v_fma_f32 v36, -v33, v35, 1.0
	v_fmac_f32_e32 v35, v36, v35
	v_mul_f32_e32 v36, v34, v35
	v_fma_f32 v37, -v33, v36, v34
	v_fmac_f32_e32 v36, v37, v35
	v_fma_f32 v33, -v33, v36, v34
	v_div_fmas_f32 v33, v33, v35, v36
	v_div_fixup_f32 v33, v33, v0, 1.0
	v_and_b32_e32 v9, 0xffff0000, v9
	v_lshlrev_b32_e32 v24, 16, v10
	v_and_b32_e32 v25, 0xffff0000, v10
	v_lshlrev_b32_e32 v10, 16, v11
	v_and_b32_e32 v11, 0xffff0000, v11
	v_mul_f32_e32 v0, v30, v33
	v_mul_f32_e32 v30, v31, v33
	v_lshlrev_b32_e32 v18, 16, v4
	v_and_b32_e32 v19, 0xffff0000, v4
	v_lshlrev_b32_e32 v4, 16, v5
	v_and_b32_e32 v5, 0xffff0000, v5
	v_lshlrev_b32_e32 v20, 16, v6
	v_and_b32_e32 v21, 0xffff0000, v6
	v_lshlrev_b32_e32 v6, 16, v7
	v_and_b32_e32 v7, 0xffff0000, v7
	v_pk_mul_f32 v[8:9], v[30:31], v[8:9] op_sel_hi:[0,1]
	v_pk_mul_f32 v[22:23], v[30:31], v[22:23] op_sel_hi:[0,1]
	v_pk_mul_f32 v[10:11], v[30:31], v[10:11] op_sel_hi:[0,1]
	v_pk_mul_f32 v[24:25], v[30:31], v[24:25] op_sel_hi:[0,1]
	v_lshlrev_b32_e32 v26, 16, v12
	v_and_b32_e32 v27, 0xffff0000, v12
	v_lshlrev_b32_e32 v12, 16, v13
	v_and_b32_e32 v13, 0xffff0000, v13
	v_lshlrev_b32_e32 v28, 16, v14
	v_and_b32_e32 v29, 0xffff0000, v14
	v_lshlrev_b32_e32 v14, 16, v15
	v_and_b32_e32 v15, 0xffff0000, v15
	v_mul_f32_e32 v32, v32, v33
	v_pk_fma_f32 v[18:19], v[0:1], v[18:19], v[22:23] op_sel_hi:[0,1,1]
	v_pk_fma_f32 v[4:5], v[0:1], v[4:5], v[8:9] op_sel_hi:[0,1,1]
	v_pk_fma_f32 v[8:9], v[0:1], v[20:21], v[24:25] op_sel_hi:[0,1,1]
	v_pk_fma_f32 v[6:7], v[0:1], v[6:7], v[10:11] op_sel_hi:[0,1,1]
	v_pk_fma_f32 v[10:11], v[32:33], v[12:13], v[4:5] op_sel_hi:[0,1,1]
	v_pk_fma_f32 v[4:5], v[32:33], v[26:27], v[18:19] op_sel_hi:[0,1,1]
	v_pk_fma_f32 v[12:13], v[32:33], v[14:15], v[6:7] op_sel_hi:[0,1,1]
	v_pk_fma_f32 v[6:7], v[32:33], v[28:29], v[8:9] op_sel_hi:[0,1,1]
	v_cvt_pk_bf16_f32 v4, v4, v5
	v_cvt_pk_bf16_f32 v5, v10, v11
	v_cvt_pk_bf16_f32 v6, v6, v7
	v_cvt_pk_bf16_f32 v7, v12, v13
	global_store_dwordx4 v[16:17], v[4:7], off
	s_andn2_b64 exec, exec, s[38:39]
	s_cbranch_execnz .LBB0_258

; __device__ __forceinline__ int ltid(int wave) { int t = (wave << 6) | (int)__builtin_amdgcn_mbcnt_hi(~0u, __builtin_amdgcn_mbcnt_lo(~0u, 0u)); asm volatile("" : "+v"(t)); return t; }
; __device__ __forceinline__ int lbid() { int b = blockIdx.x; asm volatile("" : "+s"(b)); return b; }
; __device__ __forceinline__ AttnGeom attn_geom(int it) {
;     AttnGeom G; G.hd = it / 192; const int qt = it % 192;
;     int T, lt; if (qt < 64) { G.seq_start = (qt >> 4) * 2048; T = 2048; lt = qt & 15; } else { G.seq_start = 8192; T = 16384; lt = qt - 64; }
;     const int g = G.hd >> 3; G.dil = g == 0 ? 1 : (g == 1 ? 4 : 16); G.n_lat = T / G.dil; const int tpr = G.n_lat >> 7; G.r = lt / tpr; G.q0 = (lt % tpr) << 7; return G;
; }
; __device__ void attn_items(const Params& p, unsigned char* shm) {
;     bf16_t* Ks = (bf16_t*)shm;
;     bf16_t* Vt = (bf16_t*)(shm + 36864);
;     bf16_t* Ps = (bf16_t*)(shm + 77824);
;     float* BT = (float*)(shm + 120832);
;     bf16_t* Qb = (bf16_t*)(p.ws + B_Q); const bf16_t* Kb = (const bf16_t*)(p.ws + B_K); const bf16_t* Vb = (const bf16_t*)(p.ws + B_V);
;     float* LSE = (float*)(p.ws + SM_LSE);
;     const int tid = ltid(p.wave), lane = tid & 63, w = tid >> 6, fr = lane & 15, fq = lane >> 4, G_ = gridDim.x;
;     for (int i = tid; i < 24 * 129; i += 512) { const int hd = i / 129, j = i % 129; BT[hd * 132 + j] = p.in[21][(int)BUCKET[hd >> 3][j] * 24 + hd]; }
;     u32x4 kreg[5], vreg[5]; bf16x8 q0r, q1r;
;     const int total = 24 * 192;
;     int it = lbid();
;     ...
;     if (it < total) ATT_LOAD(it);
.LBB0_326:
	s_or_b64 exec, exec, s[36:37]
	s_mov_b32 s4, s80
	s_cmpk_lt_i32 s4, 0x1200
	s_movk_i32 s0, 0x880
	s_cselect_b64 s[40:41], -1, 0
	v_ashrrev_i32_e32 v98, 3, v130
	v_cmp_gt_i32_e64 s[36:37], s0, v130
	s_movk_i32 s0, 0x100
	v_ashrrev_i32_e32 v47, 6, v130
	v_and_b32_e32 v93, 15, v130
	v_bfe_u32 v46, v130, 4, 2
	s_and_b64 vcc, exec, s[40:41]
	v_lshlrev_b32_e32 v48, 3, v130
	v_cmp_gt_i32_e64 s[38:39], s0, v98
	s_cbranch_vccz .LBB0_338
	s_mul_hi_i32 s0, s4, 0x2aaaaaab
	s_lshr_b32 s1, s0, 31
	s_ashr_i32 s0, s0, 5
	s_add_i32 s0, s0, s1
	s_mul_i32 s1, s0, 0xc0
	s_sub_i32 s1, s4, s1
	s_lshl_b32 s2, s1, 7
	s_and_b32 s3, s2, 0xfffff800
	s_and_b32 s5, s1, 15
	s_sub_i32 s6, s1, 64
	s_and_b32 s2, s0, -8
	s_cmp_eq_u32 s2, 8
	s_cselect_b32 s2, 2, 4
	s_cmp_gt_u32 s0, 7
	s_cselect_b32 s2, s2, 0
	s_cmp_lt_i32 s1, 64
	s_cselect_b32 s1, s5, s6
	s_movk_i32 s5, 0x800
	s_cselect_b32 s5, s5, 0x4000
	s_cselect_b32 s3, s3, 0x2000
	s_cselect_b32 s7, 4, 7
	s_lshr_b32 s6, s5, s2
	s_lshr_b32 s5, s6, 7
	s_sub_i32 s7, s7, s2
	s_add_i32 s5, s5, 0x1ffffff
	s_lshr_b32 s8, s1, s7
	s_and_b32 s1, s5, s1
	s_lshl_b32 s5, s1, 7
	s_sub_i32 s7, s5, 64
	v_add_u32_e32 v16, s7, v98
	s_mul_i32 s42, s0, 0x180000
	s_and_b64 s[0:1], s[36:37], s[38:39]
	v_cmp_lt_i32_e32 vcc, -1, v16
	v_mov_b32_e32 v2, v1
	v_mov_b32_e32 v3, v1
	v_mov_b32_e32 v6, v1
	v_mov_b32_e32 v7, v1
	s_ashr_i32 s43, s42, 31
	s_and_b64 s[0:1], s[0:1], vcc
	v_cmp_gt_i32_e32 vcc, s6, v16
	v_mov_b32_e32 v0, v1
	v_mov_b32_e32 v4, v1
	v_mov_b32_e32 v5, v1
	v_mov_b64_e32 v[14:15], v[6:7]
	v_mov_b64_e32 v[10:11], v[2:3]
	s_add_i32 s3, s8, s3
	v_and_or_b32 v44, v48, 56, s42
	v_mov_b32_e32 v45, s43
	s_and_b64 s[8:9], s[0:1], vcc
	v_mov_b64_e32 v[12:13], v[4:5]
	v_mov_b64_e32 v[8:9], v[0:1]
	s_and_saveexec_b64 s[0:1], s[8:9]
	s_cbranch_execz .LBB0_329
	v_lshlrev_b32_e32 v0, s2, v16
	v_add_u32_e32 v0, s3, v0
	v_mad_i64_i32 v[2:3], s[8:9], v0, 64, v[44:45]
	v_readlane_b32 s8, v252, 23
	v_lshlrev_b64 v[2:3], 1, v[2:3]
	v_readlane_b32 s9, v252, 24
	s_nop 1
	v_lshl_add_u64 v[8:9], s[8:9], 0, v[2:3]
	v_readlane_b32 s8, v252, 25
	v_readlane_b32 s9, v252, 26
	s_nop 1
	v_lshl_add_u64 v[2:3], s[8:9], 0, v[2:3]
	global_load_dwordx4 v[8:11], v[8:9], off
	s_nop 0
	global_load_dwordx4 v[12:15], v[2:3], off
.LBB0_329:
	s_or_b64 exec, exec, s[0:1]
	v_add_u32_e32 v0, 0x200, v130
	s_movk_i32 s0, 0x680
	v_ashrrev_i32_e32 v2, 3, v0
	v_cmp_gt_i32_e32 vcc, s0, v130
	s_movk_i32 s0, 0x100
	v_add_u32_e32 v0, s7, v2
	v_cmp_gt_i32_e64 s[36:37], s0, v2
	s_and_b64 s[0:1], vcc, s[36:37]
	v_cmp_lt_i32_e32 vcc, -1, v0
	s_and_b64 s[0:1], s[0:1], vcc
	v_cmp_gt_i32_e32 vcc, s6, v0
	v_mov_b64_e32 v[18:19], v[6:7]
	s_and_b64 s[8:9], s[0:1], vcc
	v_mov_b64_e32 v[16:17], v[4:5]
	s_and_saveexec_b64 s[0:1], s[8:9]
	s_cbranch_execz .LBB0_331
	v_lshlrev_b32_e32 v0, s2, v0
	v_add_u32_e32 v0, s3, v0
	v_mad_i64_i32 v[2:3], s[8:9], v0, 64, v[44:45]
	v_readlane_b32 s8, v252, 23
	v_lshlrev_b64 v[2:3], 1, v[2:3]
	v_readlane_b32 s9, v252, 24
	s_nop 1
	v_lshl_add_u64 v[4:5], s[8:9], 0, v[2:3]
	v_readlane_b32 s8, v252, 25
	v_readlane_b32 s9, v252, 26
	s_nop 1
	v_lshl_add_u64 v[2:3], s[8:9], 0, v[2:3]
	global_load_dwordx4 v[16:19], v[4:5], off
	s_nop 0
	global_load_dwordx4 v[4:7], v[2:3], off
.LBB0_331:
	s_or_b64 exec, exec, s[0:1]
	v_add_u32_e32 v0, 0x400, v130
	s_movk_i32 s0, 0x480
	v_ashrrev_i32_e32 v0, 3, v0
	v_cmp_gt_i32_e32 vcc, s0, v130
	s_movk_i32 s0, 0x100
	v_add_u32_e32 v28, s7, v0
	v_cmp_gt_i32_e64 s[36:37], s0, v0
	s_and_b64 s[0:1], vcc, s[36:37]
	v_cmp_lt_i32_e32 vcc, -1, v28
	v_mov_b32_e32 v2, v1
	v_mov_b32_e32 v3, v1
	s_and_b64 s[0:1], s[0:1], vcc
	v_cmp_gt_i32_e32 vcc, s6, v28
	v_mov_b32_e32 v0, v1
	v_mov_b64_e32 v[26:27], v[2:3]
	s_and_b64 s[8:9], s[0:1], vcc
	v_mov_b32_e32 v20, v1
	v_mov_b32_e32 v21, v1
	v_mov_b32_e32 v22, v1
	v_mov_b32_e32 v23, v1
	v_mov_b64_e32 v[24:25], v[0:1]
	s_and_saveexec_b64 s[0:1], s[8:9]
	s_cbranch_execz .LBB0_333
	v_lshlrev_b32_e32 v20, s2, v28
	v_add_u32_e32 v20, s3, v20
	v_mad_i64_i32 v[20:21], s[8:9], v20, 64, v[44:45]
	v_readlane_b32 s8, v252, 23
	v_lshlrev_b64 v[20:21], 1, v[20:21]
	v_readlane_b32 s9, v252, 24
	s_nop 1
	v_lshl_add_u64 v[22:23], s[8:9], 0, v[20:21]
	v_readlane_b32 s8, v252, 25
	v_readlane_b32 s9, v252, 26
	s_nop 1
	v_lshl_add_u64 v[24:25], s[8:9], 0, v[20:21]
	global_load_dwordx4 v[20:23], v[22:23], off
	s_nop 0
	global_load_dwordx4 v[24:27], v[24:25], off
.LBB0_333:
	s_or_b64 exec, exec, s[0:1]
	v_add_u32_e32 v28, 0x600, v130
	s_movk_i32 s0, 0x280
	v_ashrrev_i32_e32 v28, 3, v28
	v_cmp_gt_i32_e32 vcc, s0, v130
	s_movk_i32 s0, 0x100
	v_add_u32_e32 v36, s7, v28
	v_cmp_gt_i32_e64 s[36:37], s0, v28
	s_and_b64 s[0:1], vcc, s[36:37]
	v_cmp_lt_i32_e32 vcc, -1, v36
	s_and_b64 s[0:1], s[0:1], vcc
	v_cmp_gt_i32_e32 vcc, s6, v36
	v_mov_b64_e32 v[34:35], v[2:3]
	v_mov_b64_e32 v[30:31], v[2:3]
	s_and_b64 s[8:9], s[0:1], vcc
	v_mov_b64_e32 v[32:33], v[0:1]
	v_mov_b64_e32 v[28:29], v[0:1]
	s_and_saveexec_b64 s[0:1], s[8:9]
	s_cbranch_execz .LBB0_335
	v_lshlrev_b32_e32 v0, s2, v36
	v_add_u32_e32 v0, s3, v0
	v_mad_i64_i32 v[2:3], s[8:9], v0, 64, v[44:45]
	v_readlane_b32 s8, v252, 23
	v_lshlrev_b64 v[2:3], 1, v[2:3]
	v_readlane_b32 s9, v252, 24
	s_nop 1
	v_lshl_add_u64 v[28:29], s[8:9], 0, v[2:3]
	v_readlane_b32 s8, v252, 25
	v_readlane_b32 s9, v252, 26
	s_nop 1
	v_lshl_add_u64 v[2:3], s[8:9], 0, v[2:3]
	global_load_dwordx4 v[28:31], v[28:29], off
	s_nop 0
	global_load_dwordx4 v[32:35], v[2:3], off
.LBB0_335:
	s_or_b64 exec, exec, s[0:1]
	v_add_u32_e32 v0, 0x800, v130
	s_movk_i32 s0, 0x80
	v_ashrrev_i32_e32 v0, 3, v0
	v_cmp_gt_i32_e32 vcc, s0, v130
	s_movk_i32 s0, 0x100
	v_add_u32_e32 v49, s7, v0
	v_cmp_gt_i32_e64 s[36:37], s0, v0
	s_and_b64 s[0:1], vcc, s[36:37]
	v_cmp_lt_i32_e32 vcc, -1, v49
	v_mov_b32_e32 v2, v1
	v_mov_b32_e32 v3, v1
	s_and_b64 s[0:1], s[0:1], vcc
	v_cmp_gt_i32_e32 vcc, s6, v49
	v_mov_b32_e32 v0, v1
	v_mov_b64_e32 v[42:43], v[2:3]
	s_and_b64 s[6:7], s[0:1], vcc
	v_mov_b32_e32 v36, v1
	v_mov_b32_e32 v37, v1
	v_mov_b32_e32 v38, v1
	v_mov_b32_e32 v39, v1
	v_mov_b64_e32 v[40:41], v[0:1]
	s_and_saveexec_b64 s[0:1], s[6:7]
	s_cbranch_execz .LBB0_337
	v_lshlrev_b32_e32 v0, s2, v49
	v_add_u32_e32 v0, s3, v0
	v_mad_i64_i32 v[2:3], s[6:7], v0, 64, v[44:45]
	v_readlane_b32 s6, v252, 23
	v_lshlrev_b64 v[2:3], 1, v[2:3]
	v_readlane_b32 s7, v252, 24
	s_nop 1
	v_lshl_add_u64 v[36:37], s[6:7], 0, v[2:3]
	v_readlane_b32 s6, v252, 25
	v_readlane_b32 s7, v252, 26
	s_nop 1
	v_lshl_add_u64 v[2:3], s[6:7], 0, v[2:3]
	global_load_dwordx4 v[40:43], v[36:37], off
	s_nop 0
	global_load_dwordx4 v[36:39], v[2:3], off
.LBB0_337:
	s_or_b64 exec, exec, s[0:1]
	v_lshl_add_u32 v0, v47, 4, s5
	v_or_b32_e32 v0, v0, v93
	v_lshlrev_b32_e32 v0, s2, v0
	v_add_u32_e32 v0, s3, v0
	v_mov_b64_e32 v[2:3], s[90:91]
	s_movk_i32 s8, 0x80
	v_mad_i64_i32 v[2:3], s[0:1], v0, s8, v[2:3]
	v_lshl_add_u64 v[2:3], s[42:43], 1, v[2:3]
	v_lshlrev_b32_e32 v0, 4, v46
	v_lshl_add_u64 v[2:3], v[2:3], 0, v[0:1]
	global_load_dwordx4 v[56:59], v[2:3], off
	global_load_dwordx4 v[52:55], v[2:3], off offset:64

; __device__ void attn_items(const Params& p, unsigned char* shm) {
;     ...
;         for (int h = 0; h < 2; ++h) { const int c = lane + 64 * h, row = c >> 3, c8 = c & 7;
;             *(u32x4*)(Qb + (size_t)(G.seq_start + G.r + G.dil * (G.q0 + 16 * w + row)) * 1536 + G.hd * 64 + c8 * 8) = *(const u32x4*)(Pw + row * 168 + c8 * 8); }
;         __syncthreads();
.LBB0_340:
	s_or_b64 exec, exec, s[0:1]
	s_waitcnt lgkmcnt(0)
	s_barrier
	ds_read_b128 v[52:55], v173
	s_mul_i32 s0, s58, 0x180000
	v_or_b32_e32 v56, v0, v109
	s_ashr_i32 s1, s0, 31
	v_lshlrev_b32_e32 v56, s4, v56
	v_lshl_add_u64 v[2:3], s[0:1], 1, v[94:95]
	v_add_u32_e32 v56, s6, v56
	s_movk_i32 s5, 0x80
	v_mad_i64_i32 v[56:57], s[0:1], v56, s5, v[2:3]
	s_waitcnt lgkmcnt(0)
	global_store_dwordx4 v[56:57], v[52:55], off
	ds_read_b128 v[52:55], v174
	v_or_b32_e32 v0, v0, v149
	v_lshlrev_b32_e32 v0, s4, v0
	v_add_u32_e32 v0, s6, v0
	v_mad_i64_i32 v[2:3], s[0:1], v0, s5, v[2:3]
	s_waitcnt lgkmcnt(0)
	global_store_dwordx4 v[2:3], v[52:55], off
	s_waitcnt vmcnt(3)
	v_mov_b64_e32 v[58:59], v[46:47]
	s_movk_i32 s22, 0xc00
	s_waitcnt vmcnt(2)
	v_mov_b64_e32 v[54:55], v[50:51]
	s_add_i32 s2, s2, s3
	s_and_b64 vcc, exec, s[40:41]
	v_mov_b64_e32 v[56:57], v[44:45]
	v_mov_b64_e32 v[52:53], v[48:49]
	s_mov_b32 s4, s15
	s_barrier
	s_cbranch_vccnz .LBB0_793

; __device__ void attn_items(const Params& p, unsigned char* shm) {
;     ...
;     if (it < total) ATT_LOAD(it);
;     ...
;         if (it + G_ < total) ATT_LOAD(it + G_);
.LBB0_361:
	s_or_b64 exec, exec, s[0:1]
	v_readlane_b32 s0, v251, 10
	s_add_i32 s15, s4, s0
	s_cmpk_gt_i32 s15, 0x11ff
	s_cselect_b64 s[40:41], -1, 0
	s_waitcnt vmcnt(1)
	v_mov_b64_e32 v[44:45], v[56:57]
	s_waitcnt vmcnt(0)
	v_mov_b64_e32 v[48:49], v[52:53]
	s_and_b64 vcc, exec, s[40:41]
	v_mov_b64_e32 v[46:47], v[58:59]
	v_mov_b64_e32 v[50:51], v[54:55]
	s_waitcnt lgkmcnt(0)
	s_barrier
	v_readlane_b32 s1, v251, 11
	s_cbranch_vccnz .LBB0_373
	s_mul_hi_i32 s0, s15, 0x2aaaaaab
	s_lshr_b32 s1, s0, 31
	s_ashr_i32 s0, s0, 5
	s_add_i32 s0, s0, s1
	s_mul_i32 s1, s0, 0xffffff40
	s_mul_i32 s5, s0, 0xffffa000
	s_add_i32 s6, s3, s2
	s_add_i32 s1, s15, s1
	s_add_i32 s6, s6, s5
	s_and_b32 s6, s6, 0xfffff800
	s_and_b32 s7, s1, 15
	s_sub_i32 s8, s1, 64
	s_and_b32 s5, s0, -8
	s_cmp_eq_u32 s5, 8
	s_cselect_b32 s5, 2, 4
	s_cmp_gt_u32 s0, 7
	s_cselect_b32 s5, s5, 0
	s_cmp_lt_i32 s1, 64
	s_cselect_b32 s1, s7, s8
	s_movk_i32 s7, 0x800
	s_cselect_b32 s7, s7, 0x4000
	s_cselect_b32 s10, s6, 0x2000
	s_cselect_b32 s6, 4, 7
	s_lshr_b32 s8, s7, s5
	s_lshr_b32 s7, s8, 7
	s_sub_i32 s6, s6, s5
	s_add_i32 s7, s7, -1
	s_lshr_b32 s17, s1, s6
	s_and_b32 s1, s7, s1
	s_lshl_b32 s6, s1, 7
	s_sub_i32 s9, s6, 64
	s_mul_i32 s38, s0, 0x180000
	v_add_u32_e32 v16, s9, v98
	v_readlane_b32 s0, v255, 14
	v_cmp_lt_i32_e32 vcc, -1, v16
	v_readlane_b32 s1, v255, 15
	v_mov_b32_e32 v2, v1
	v_mov_b32_e32 v3, v1
	v_mov_b32_e32 v6, v1
	v_mov_b32_e32 v7, v1
	s_ashr_i32 s39, s38, 31
	s_and_b64 s[0:1], s[0:1], vcc
	v_cmp_gt_i32_e32 vcc, s8, v16
	v_mov_b32_e32 v0, v1
	v_mov_b32_e32 v4, v1
	v_mov_b32_e32 v5, v1
	v_mov_b64_e32 v[14:15], v[6:7]
	v_mov_b64_e32 v[10:11], v[2:3]
	s_add_i32 s7, s17, s10
	v_mov_b32_e32 v45, s39
	v_or_b32_e32 v44, s38, v92
	s_and_b64 s[18:19], s[0:1], vcc
	v_mov_b64_e32 v[12:13], v[4:5]
	v_mov_b64_e32 v[8:9], v[0:1]
	s_and_saveexec_b64 s[0:1], s[18:19]
	s_cbranch_execz .LBB0_364
	v_lshlrev_b32_e32 v0, s5, v16
	v_add_u32_e32 v0, s7, v0
	v_mad_i64_i32 v[2:3], s[18:19], v0, 64, v[44:45]
	v_readlane_b32 s18, v252, 23
	v_lshlrev_b64 v[2:3], 1, v[2:3]
	v_readlane_b32 s19, v252, 24
	s_nop 1
	v_lshl_add_u64 v[8:9], s[18:19], 0, v[2:3]
	v_readlane_b32 s18, v252, 25
	v_readlane_b32 s19, v252, 26
	s_nop 1
	v_lshl_add_u64 v[2:3], s[18:19], 0, v[2:3]
	global_load_dwordx4 v[8:11], v[8:9], off
	s_nop 0
	global_load_dwordx4 v[12:15], v[2:3], off
.LBB0_364:
	s_or_b64 exec, exec, s[0:1]
	v_add_u32_e32 v0, s9, v110
	v_readlane_b32 s0, v255, 18
	v_cmp_lt_i32_e32 vcc, -1, v0
	v_readlane_b32 s1, v255, 19
	s_and_b64 s[0:1], s[0:1], vcc
	v_cmp_gt_i32_e32 vcc, s8, v0
	v_mov_b64_e32 v[18:19], v[6:7]
	s_and_b64 s[18:19], s[0:1], vcc
	v_mov_b64_e32 v[16:17], v[4:5]
	s_and_saveexec_b64 s[0:1], s[18:19]
	s_cbranch_execz .LBB0_366
	v_lshlrev_b32_e32 v0, s5, v0
	v_add_u32_e32 v0, s7, v0
	v_mad_i64_i32 v[2:3], s[18:19], v0, 64, v[44:45]
	v_readlane_b32 s18, v252, 23
	v_lshlrev_b64 v[2:3], 1, v[2:3]
	v_readlane_b32 s19, v252, 24
	s_nop 1
	v_lshl_add_u64 v[4:5], s[18:19], 0, v[2:3]
	v_readlane_b32 s18, v252, 25
	v_readlane_b32 s19, v252, 26
	s_nop 1
	v_lshl_add_u64 v[2:3], s[18:19], 0, v[2:3]
	global_load_dwordx4 v[16:19], v[4:5], off
	s_nop 0
	global_load_dwordx4 v[4:7], v[2:3], off
.LBB0_366:
	s_or_b64 exec, exec, s[0:1]
	v_add_u32_e32 v28, s9, v111
	v_readlane_b32 s0, v255, 22
	v_cmp_lt_i32_e32 vcc, -1, v28
	v_readlane_b32 s1, v255, 23
	v_mov_b32_e32 v2, v1
	v_mov_b32_e32 v3, v1
	s_and_b64 s[0:1], s[0:1], vcc
	v_cmp_gt_i32_e32 vcc, s8, v28
	v_mov_b32_e32 v0, v1
	v_mov_b64_e32 v[26:27], v[2:3]
	s_and_b64 s[18:19], s[0:1], vcc
	v_mov_b32_e32 v20, v1
	v_mov_b32_e32 v21, v1
	v_mov_b32_e32 v22, v1
	v_mov_b32_e32 v23, v1
	v_mov_b64_e32 v[24:25], v[0:1]
	s_and_saveexec_b64 s[0:1], s[18:19]
	s_cbranch_execz .LBB0_368
	v_lshlrev_b32_e32 v20, s5, v28
	v_add_u32_e32 v20, s7, v20
	v_mad_i64_i32 v[20:21], s[18:19], v20, 64, v[44:45]
	v_readlane_b32 s18, v252, 23
	v_lshlrev_b64 v[20:21], 1, v[20:21]
	v_readlane_b32 s19, v252, 24
	s_nop 1
	v_lshl_add_u64 v[22:23], s[18:19], 0, v[20:21]
	v_readlane_b32 s18, v252, 25
	v_readlane_b32 s19, v252, 26
	s_nop 1
	v_lshl_add_u64 v[24:25], s[18:19], 0, v[20:21]
	global_load_dwordx4 v[20:23], v[22:23], off
	s_nop 0
	global_load_dwordx4 v[24:27], v[24:25], off
.LBB0_368:
	s_or_b64 exec, exec, s[0:1]
	v_add_u32_e32 v36, s9, v112
	v_readlane_b32 s0, v255, 26
	v_cmp_lt_i32_e32 vcc, -1, v36
	v_readlane_b32 s1, v255, 27
	s_and_b64 s[0:1], s[0:1], vcc
	v_cmp_gt_i32_e32 vcc, s8, v36
	v_mov_b64_e32 v[34:35], v[2:3]
	v_mov_b64_e32 v[30:31], v[2:3]
	s_and_b64 s[18:19], s[0:1], vcc
	v_mov_b64_e32 v[32:33], v[0:1]
	v_mov_b64_e32 v[28:29], v[0:1]
	s_and_saveexec_b64 s[0:1], s[18:19]
	s_cbranch_execz .LBB0_370
	v_lshlrev_b32_e32 v0, s5, v36
	v_add_u32_e32 v0, s7, v0
	v_mad_i64_i32 v[2:3], s[18:19], v0, 64, v[44:45]
	v_readlane_b32 s18, v252, 23
	v_lshlrev_b64 v[2:3], 1, v[2:3]
	v_readlane_b32 s19, v252, 24
	s_nop 1
	v_lshl_add_u64 v[28:29], s[18:19], 0, v[2:3]
	v_readlane_b32 s18, v252, 25
	v_readlane_b32 s19, v252, 26
	s_nop 1
	v_lshl_add_u64 v[2:3], s[18:19], 0, v[2:3]
	global_load_dwordx4 v[28:31], v[28:29], off
	s_nop 0
	global_load_dwordx4 v[32:35], v[2:3], off
.LBB0_370:
	s_or_b64 exec, exec, s[0:1]
	v_add_u32_e32 v46, s9, v113
	v_readlane_b32 s0, v255, 30
	v_cmp_lt_i32_e32 vcc, -1, v46
	v_readlane_b32 s1, v255, 31
	v_mov_b32_e32 v2, v1
	v_mov_b32_e32 v3, v1
	s_and_b64 s[0:1], s[0:1], vcc
	v_cmp_gt_i32_e32 vcc, s8, v46
	v_mov_b32_e32 v0, v1
	v_mov_b64_e32 v[42:43], v[2:3]
	s_and_b64 s[8:9], s[0:1], vcc
	v_mov_b32_e32 v36, v1
	v_mov_b32_e32 v37, v1
	v_mov_b32_e32 v38, v1
	v_mov_b32_e32 v39, v1
	v_mov_b64_e32 v[40:41], v[0:1]
	s_and_saveexec_b64 s[0:1], s[8:9]
	s_cbranch_execz .LBB0_372
	v_lshlrev_b32_e32 v0, s5, v46
	v_add_u32_e32 v0, s7, v0
	v_mad_i64_i32 v[2:3], s[8:9], v0, 64, v[44:45]
	v_readlane_b32 s8, v252, 23
	v_lshlrev_b64 v[2:3], 1, v[2:3]
	v_readlane_b32 s9, v252, 24
	s_nop 1
	v_lshl_add_u64 v[36:37], s[8:9], 0, v[2:3]
	v_readlane_b32 s8, v252, 25
	v_readlane_b32 s9, v252, 26
	s_nop 1
	v_lshl_add_u64 v[2:3], s[8:9], 0, v[2:3]
	global_load_dwordx4 v[40:43], v[36:37], off
	s_nop 0
	global_load_dwordx4 v[36:39], v[2:3], off
.LBB0_372:
	s_or_b64 exec, exec, s[0:1]
	v_add_u32_e32 v0, s6, v100
	v_lshlrev_b32_e32 v0, s5, v0
	v_add_u32_e32 v0, s7, v0
	v_mov_b64_e32 v[2:3], s[86:87]
	s_movk_i32 s8, 0x80
	v_mad_i64_i32 v[2:3], s[0:1], v0, s8, v[2:3]
	v_lshl_add_u64 v[2:3], s[38:39], 1, v[2:3]
	v_mov_b32_e32 v97, v1
	v_lshl_add_u64 v[2:3], v[2:3], 0, v[96:97]
	global_load_dwordx4 v[44:47], v[2:3], off
	global_load_dwordx4 v[48:51], v[2:3], off offset:64

;     __device__ __forceinline__ void operator()(AccRef acc, const Unit& u, int wr, int wc, int fr, int fq, const float (&pre)[8]) const {
;         const int pn = u.pn; int act, ld, cb; size_t base;
;         if (pn < 4) { act = 0; ld = 1024; cb = pn * 256; base = B_XL; }
;         else if (pn < 8) { act = 1; ld = 1024; cb = (pn - 4) * 256; base = B_GL; }
;         else if (pn < 12) { act = 2; ld = 0; cb = (pn - 8) * 256; base = B_A2; }
;         else if (pn < 18) { act = 3; ld = 1536; cb = (pn - 12) * 256; base = B_Q; }
;         else if (pn < 24) { act = 0; ld = 1536; cb = (pn - 18) * 256; base = B_K; }
;         else if (pn < 30) { act = 0; ld = 1536; cb = (pn - 24) * 256; base = B_V; }
;         else if (pn < 38) { act = 4; ld = 2048; cb = (pn - 30) * 256; base = B_GA; }
;         else if (pn < 46) { act = 4; ld = 2048; cb = (pn - 38) * 256; base = B_GB; }
;         else { act = 4; ld = 2048; cb = (pn - 46) * 256; base = B_GC; }
;         bf16_t* O = (bf16_t*)(ws + base);
;         const int row0 = u.pm * BM + wr * 64 + fr, col0 = cb + wc * 32 + 8 * fq;
; #pragma unroll
;         for (int ai = 0; ai < 2; ++ai)
; #pragma unroll
;             for (int m = 0; m < 4; ++m)
; #pragma unroll
;                 for (int bj = 0; bj < 2; ++bj) {
;                     const int row = row0 + ai * HALF + m * 16, col = col0 + bj * HALF;
;                     const float r = pre[ai * 4 + m]; f32x4 v0 = acc[ai][bj][m][0], v1 = acc[ai][bj][m][1];
;                     if (act == 1) { v0 *= r; v1 *= r;
;                         const f32x2 o0 = gelu2((f32x2){v0[0], v0[1]}), o1 = gelu2((f32x2){v0[2], v0[3]}), o2 = gelu2((f32x2){v1[0], v1[1]}), o3 = gelu2((f32x2){v1[2], v1[3]});
;                         v0 = (f32x4){o0.x, o0.y, o1.x, o1.y}; v1 = (f32x4){o2.x, o2.y, o3.x, o3.y}; }
;                     else if (act == 4) { const float rn = r * -1.4426950408889634f;
;                         const f32x2 o0 = sigm2((f32x2){v0[0], v0[1]}, rn), o1 = sigm2((f32x2){v0[2], v0[3]}, rn), o2 = sigm2((f32x2){v1[0], v1[1]}, rn), o3 = sigm2((f32x2){v1[2], v1[3]}, rn);
;                         v0 = (f32x4){o0.x, o0.y, o1.x, o1.y}; v1 = (f32x4){o2.x, o2.y, o3.x, o3.y}; }
;                     else { const float rr = act == 3 ? r * 0.125f : r; v0 *= rr; v1 *= rr; }
;                     size_t off;
.LBB0_556:
	s_cmp_eq_u32 s64, 0x600
	s_cselect_b32 s64, 64, s64
	s_cselect_b32 s0, 0x180000, 64
	v_add_u32_e32 v130, s2, v203
	v_lshrrev_b32_e32 v146, 6, v130
	v_and_b32_e32 v130, 63, v130
	v_mad_u32_u24 v130, v146, s0, v130
	s_lshl_b32 s3, s22, 8
	s_add_i32 s3, s3, s33
	v_or_b32_e32 v149, s3, v191
	s_ashr_i32 s0, s3, 31
	s_xor_b64 s[60:61], s[40:41], -1
	s_mul_i32 s2, s64, s0
	v_mul_lo_u32 v131, s65, v149
	v_mad_u64_u32 v[134:135], s[0:1], s64, v149, 0
	v_add3_u32 v135, v135, s2, v131
	s_mov_b64 s[0:1], -1
	s_and_b64 vcc, exec, s[60:61]
	v_ashrrev_i32_e32 v131, 31, v130
	s_cbranch_vccz .LBB0_558
	v_lshl_add_u64 v[142:143], v[134:135], 0, v[130:131]
	s_mov_b64 s[0:1], 0

; __device__ __forceinline__ f32x2 gelu2(f32x2 v) { const f32x2 z = v * ((v * v) * (-0.10294324f) + (-2.3022082f)); return v * rcp_2(exp2_2(z) + 1.0f); }
; __device__ __forceinline__ f32x2 sigm2(f32x2 a, float rn) { return rcp_2(exp2_2(a * rn) + 1.0f); }
;     __device__ __forceinline__ void operator()(AccRef acc, const Unit& u, int wr, int wc, int fr, int fq, const float (&pre)[8]) const {
;     ...
;                 for (int bj = 0; bj < 2; ++bj) {
;                     const int row = row0 + ai * HALF + m * 16, col = col0 + bj * HALF;
;                     const float r = pre[ai * 4 + m]; f32x4 v0 = acc[ai][bj][m][0], v1 = acc[ai][bj][m][1];
;                     if (act == 1) { v0 *= r; v1 *= r;
;                         const f32x2 o0 = gelu2((f32x2){v0[0], v0[1]}), o1 = gelu2((f32x2){v0[2], v0[3]}), o2 = gelu2((f32x2){v1[0], v1[1]}), o3 = gelu2((f32x2){v1[2], v1[3]});
;                         v0 = (f32x4){o0.x, o0.y, o1.x, o1.y}; v1 = (f32x4){o2.x, o2.y, o3.x, o3.y}; }
;                     else if (act == 4) { const float rn = r * -1.4426950408889634f;
;                         const f32x2 o0 = sigm2((f32x2){v0[0], v0[1]}, rn), o1 = sigm2((f32x2){v0[2], v0[3]}, rn), o2 = sigm2((f32x2){v1[0], v1[1]}, rn), o3 = sigm2((f32x2){v1[2], v1[3]}, rn);
;                         v0 = (f32x4){o0.x, o0.y, o1.x, o1.y}; v1 = (f32x4){o2.x, o2.y, o3.x, o3.y}; }
;                     else { const float rr = act == 3 ? r * 0.125f : r; v0 *= rr; v1 *= rr; }
;                     size_t off;
;                     if (act == 2) off = ((size_t)(col >> 4) * NSUB + (row >> 4)) * 512 + (row & 15) * 16 + (col & 15);
;                     else off = (size_t)row * ld + col;
.LBB0_568:
	s_movk_i32 s0, 0x80
	s_cmp_eq_u32 s64, 64
	s_cselect_b32 s0, 0x300000, s0
	v_add_u32_e32 v132, s0, v130
	v_cndmask_b32_e64 v133, 0, 1, s[60:61]
	s_mov_b64 s[0:1], -1
	v_cmp_ne_u32_e64 s[42:43], 1, v133
	s_andn2_b64 vcc, exec, s[60:61]
	v_ashrrev_i32_e32 v133, 31, v132
	s_cbranch_vccnz .LBB0_570
	v_lshl_add_u64 v[144:145], v[134:135], 0, v[132:133]
	s_mov_b64 s[0:1], 0
